# v36 + up-GEMM silu epilogue instruction selection: cvt_pk writes the store staging quad directly (32 v_mov removed), scalar mul/add pairs -> v_pk_mul_f32/v_pk_add_f32 (31 pairs), exact
# baseline (speedup 1.0000x reference)
; __device__ __forceinline__ unsigned pk2(float lo, float hi) { const f32x2v v = {lo, hi}; const bf16x2v r = __builtin_convertvector(v, bf16x2v); return __builtin_bit_cast(unsigned, r); }
; __device__ __forceinline__ float silu_f(float x) { return x * __builtin_amdgcn_rcpf(1.f + __expf(-x)); }
; #define GEMM_EPI_LOOP _Pragma("unroll") for (int ai = 0; ai < 2; ++ai) _Pragma("unroll") for (int m = 0; m < 4; ++m) _Pragma("unroll") for (int bj = 0; bj < 2; ++bj)
; __device__ __forceinline__ void gemm_up_phase(const bf16_t* a, const bf16_t* wgu, bf16_t* act, char* lds) {
;   gemm_phase(a, 1024, wgu, 1024, 1024, NGU / 256, lds, [&](f32x4 (&acc)[2][2][4][2], int tm, int tn) {
;     GEMM_LANE;
;     GEMM_EPI_LOOP {
;       const int row = tm * 256 + ai * 128 + wr * 64 + m * 16 + fr;
;       const int col = tn * 128 + bj * 64 + wc * 16 + 4 * fq;
;       const f32x4 g = acc[ai][bj][m][0], u = acc[ai][bj][m][1];
;       u32x2 o; o.x = pk2(silu_f(g[0]) * u[0], silu_f(g[1]) * u[1]); o.y = pk2(silu_f(g[2]) * u[2], silu_f(g[3]) * u[3]);
;       *(u32x2*)(act + (size_t)row * DFF + col) = o;
;     }
.LBB0_645:
	v_mov_b32_e32 v138, 0xbfb8aa3b
	v_mov_b32_e32 v172, 1.0
	v_mov_b32 v129, v179
	s_lshl_b32 s1, s34, 8
	v_ashrrev_i32_e32 v128, 2, v129
	v_and_b32_e32 v128, 0xffffffc0, v128
	v_and_or_b32 v130, v129, 15, s1
	s_lshl_b32 s0, s0, 7
	v_lshrrev_b32_e32 v129, 2, v129
	v_add_u32_e32 v128, v130, v128
	v_lshrrev_b32_e32 v131, 1, v179
	v_and_b32_e32 v131, 0x60, v131
	v_and_or_b32 v130, v129, 8, s0
	v_or_b32_e32 v130, v130, v131
	v_and_b32_e32 v131, 16, v179
	v_or_b32_e32 v130, v130, v131
	v_mul_f32_e32 v129, 0xbfb8aa3b, v124
	v_exp_f32_e32 v129, v129
	v_ashrrev_i32_e32 v131, 31, v130
	s_andn2_b64 vcc, exec, s[38:39]
	s_mov_b32 s34, s36
	v_add_f32_e32 v129, 1.0, v129
	v_rcp_f32_e32 v132, v129
	v_mul_f32_e32 v129, 0xbfb8aa3b, v125
	v_exp_f32_e32 v129, v129
	s_nop 0
	v_add_f32_e32 v129, 1.0, v129
	v_rcp_f32_e32 v133, v129
	s_nop 0
	v_pk_mul_f32 v[124:125], v[124:125], v[132:133]
	s_nop 0
	v_pk_mul_f32 v[120:121], v[120:121], v[124:125]
	s_nop 0
	v_cvt_pk_bf16_f32 v140, v120, v121
	v_pk_mul_f32 v[120:121], v[126:127], v[138:139] op_sel_hi:[1,0]
	s_nop 0
	v_exp_f32_e32 v120, v120
	v_exp_f32_e32 v121, v121
	s_nop 0
	v_pk_add_f32 v[120:121], v[120:121], v[172:173] op_sel_hi:[1,0]
	s_nop 0
	v_rcp_f32_e32 v120, v120
	v_rcp_f32_e32 v121, v121
	s_nop 0
	v_pk_mul_f32 v[120:121], v[126:127], v[120:121]
	s_nop 0
	v_pk_mul_f32 v[120:121], v[122:123], v[120:121]
	v_lshlrev_b64 v[122:123], 1, v[130:131]
	v_cvt_pk_bf16_f32 v141, v120, v121
	v_mov_b64_e32 v[120:121], s[84:85]
	v_mad_i64_i32 v[126:127], s[0:1], v128, s3, v[120:121]
	v_lshl_add_u64 v[126:127], v[126:127], 0, v[122:123]
	v_pk_mul_f32 v[124:125], v[116:117], v[138:139] op_sel_hi:[1,0]
	s_nop 0
	v_exp_f32_e32 v124, v124
	v_exp_f32_e32 v125, v125
	s_nop 0
	v_pk_add_f32 v[124:125], v[124:125], v[172:173] op_sel_hi:[1,0]
	s_nop 0
	v_rcp_f32_e32 v124, v124
	v_rcp_f32_e32 v125, v125
	s_nop 0
	v_pk_mul_f32 v[116:117], v[116:117], v[124:125]
	s_nop 0
	v_pk_mul_f32 v[112:113], v[112:113], v[116:117]
	s_nop 0
	v_cvt_pk_bf16_f32 v142, v112, v113
	v_pk_mul_f32 v[116:117], v[118:119], v[138:139] op_sel_hi:[1,0]
	s_nop 0
	v_exp_f32_e32 v116, v116
	v_exp_f32_e32 v117, v117
	s_nop 0
	v_pk_add_f32 v[116:117], v[116:117], v[172:173] op_sel_hi:[1,0]
	s_nop 0
	v_rcp_f32_e32 v116, v116
	v_rcp_f32_e32 v117, v117
	s_nop 0
	v_pk_mul_f32 v[116:117], v[118:119], v[116:117]
	s_nop 0
	v_pk_mul_f32 v[114:115], v[114:115], v[116:117]
	s_nop 0
	v_cvt_pk_bf16_f32 v143, v114, v115
	s_nop 1
	v_permlane16_swap_b32_e32 v140, v142
	v_permlane16_swap_b32_e32 v141, v143
	global_store_dwordx4 v[126:127], v[140:143], off
	v_pk_mul_f32 v[112:113], v[108:109], v[138:139] op_sel_hi:[1,0]
	s_nop 0
	v_exp_f32_e32 v112, v112
	v_exp_f32_e32 v113, v113
	v_or_b32_e32 v114, 16, v128
	v_pk_add_f32 v[112:113], v[112:113], v[172:173] op_sel_hi:[1,0]
	s_nop 0
	v_rcp_f32_e32 v112, v112
	v_rcp_f32_e32 v113, v113
	s_nop 0
	v_pk_mul_f32 v[108:109], v[108:109], v[112:113]
	s_nop 0
	v_pk_mul_f32 v[104:105], v[104:105], v[108:109]
	s_nop 0
	v_cvt_pk_bf16_f32 v144, v104, v105
	v_pk_mul_f32 v[108:109], v[110:111], v[138:139] op_sel_hi:[1,0]
	s_nop 0
	v_exp_f32_e32 v108, v108
	v_exp_f32_e32 v109, v109
	s_nop 0
	v_pk_add_f32 v[108:109], v[108:109], v[172:173] op_sel_hi:[1,0]
	s_nop 0
	v_rcp_f32_e32 v108, v108
	v_rcp_f32_e32 v109, v109
	s_nop 0
	v_pk_mul_f32 v[108:109], v[110:111], v[108:109]
	s_nop 0
	v_pk_mul_f32 v[106:107], v[106:107], v[108:109]
	s_nop 0
	v_cvt_pk_bf16_f32 v145, v106, v107
	v_mad_i64_i32 v[106:107], s[0:1], v114, s3, v[120:121]
	v_lshl_add_u64 v[106:107], v[106:107], 0, v[122:123]
	v_pk_mul_f32 v[104:105], v[100:101], v[138:139] op_sel_hi:[1,0]
	s_nop 0
	v_exp_f32_e32 v104, v104
	v_exp_f32_e32 v105, v105
	s_nop 0
	v_pk_add_f32 v[104:105], v[104:105], v[172:173] op_sel_hi:[1,0]
	s_nop 0
	v_rcp_f32_e32 v104, v104
	v_rcp_f32_e32 v105, v105
	s_nop 0
	v_pk_mul_f32 v[100:101], v[100:101], v[104:105]
	s_nop 0
	v_pk_mul_f32 v[96:97], v[96:97], v[100:101]
	s_nop 0
	v_cvt_pk_bf16_f32 v146, v96, v97
	v_pk_mul_f32 v[100:101], v[102:103], v[138:139] op_sel_hi:[1,0]
	s_nop 0
	v_exp_f32_e32 v100, v100
	v_exp_f32_e32 v101, v101
	s_nop 0
	v_pk_add_f32 v[100:101], v[100:101], v[172:173] op_sel_hi:[1,0]
	s_nop 0
	v_rcp_f32_e32 v100, v100
	v_rcp_f32_e32 v101, v101
	s_nop 0
	v_pk_mul_f32 v[100:101], v[102:103], v[100:101]
	s_nop 0
	v_pk_mul_f32 v[98:99], v[98:99], v[100:101]
	s_nop 0
	v_cvt_pk_bf16_f32 v147, v98, v99
	s_nop 1
	v_permlane16_swap_b32_e32 v144, v146
	v_permlane16_swap_b32_e32 v145, v147
	global_store_dwordx4 v[106:107], v[144:147], off
	v_pk_mul_f32 v[96:97], v[92:93], v[138:139] op_sel_hi:[1,0]
	s_nop 0
	v_exp_f32_e32 v96, v96
	v_exp_f32_e32 v97, v97
	v_or_b32_e32 v98, 32, v128
	v_pk_add_f32 v[96:97], v[96:97], v[172:173] op_sel_hi:[1,0]
	s_nop 0
	v_rcp_f32_e32 v96, v96
	v_rcp_f32_e32 v97, v97
	s_nop 0
	v_pk_mul_f32 v[92:93], v[92:93], v[96:97]
	s_nop 0
	v_pk_mul_f32 v[88:89], v[88:89], v[92:93]
	s_nop 0
	v_cvt_pk_bf16_f32 v148, v88, v89
	v_pk_mul_f32 v[92:93], v[94:95], v[138:139] op_sel_hi:[1,0]
	s_nop 0
	v_exp_f32_e32 v92, v92
	v_exp_f32_e32 v93, v93
	s_nop 0
	v_pk_add_f32 v[92:93], v[92:93], v[172:173] op_sel_hi:[1,0]
	s_nop 0
	v_rcp_f32_e32 v92, v92
	v_rcp_f32_e32 v93, v93
	s_nop 0
	v_pk_mul_f32 v[92:93], v[94:95], v[92:93]
	s_nop 0
	v_pk_mul_f32 v[90:91], v[90:91], v[92:93]
	s_nop 0
	v_cvt_pk_bf16_f32 v149, v90, v91
	v_mad_i64_i32 v[90:91], s[0:1], v98, s3, v[120:121]
	v_lshl_add_u64 v[90:91], v[90:91], 0, v[122:123]
	v_pk_mul_f32 v[88:89], v[84:85], v[138:139] op_sel_hi:[1,0]
	s_nop 0
	v_exp_f32_e32 v88, v88
	v_exp_f32_e32 v89, v89
	s_nop 0
	v_pk_add_f32 v[88:89], v[88:89], v[172:173] op_sel_hi:[1,0]
	s_nop 0
	v_rcp_f32_e32 v88, v88
; __device__ __forceinline__ unsigned pk2(float lo, float hi) { const f32x2v v = {lo, hi}; const bf16x2v r = __builtin_convertvector(v, bf16x2v); return __builtin_bit_cast(unsigned, r); }
; __device__ __forceinline__ float silu_f(float x) { return x * __builtin_amdgcn_rcpf(1.f + __expf(-x)); }
; #define GEMM_EPI_LOOP _Pragma("unroll") for (int ai = 0; ai < 2; ++ai) _Pragma("unroll") for (int m = 0; m < 4; ++m) _Pragma("unroll") for (int bj = 0; bj < 2; ++bj)
; __device__ __forceinline__ void gemm_up_phase(const bf16_t* a, const bf16_t* wgu, bf16_t* act, char* lds) {
;   gemm_phase(a, 1024, wgu, 1024, 1024, NGU / 256, lds, [&](f32x4 (&acc)[2][2][4][2], int tm, int tn) {
;     GEMM_LANE;
;     GEMM_EPI_LOOP {
;       const int row = tm * 256 + ai * 128 + wr * 64 + m * 16 + fr;
;       const int col = tn * 128 + bj * 64 + wc * 16 + 4 * fq;
;       const f32x4 g = acc[ai][bj][m][0], u = acc[ai][bj][m][1];
;       u32x2 o; o.x = pk2(silu_f(g[0]) * u[0], silu_f(g[1]) * u[1]); o.y = pk2(silu_f(g[2]) * u[2], silu_f(g[3]) * u[3]);
;       *(u32x2*)(act + (size_t)row * DFF + col) = o;
;     }
	v_rcp_f32_e32 v89, v89
	s_nop 0
	v_pk_mul_f32 v[84:85], v[84:85], v[88:89]
	s_nop 0
	v_pk_mul_f32 v[80:81], v[80:81], v[84:85]
	s_nop 0
	v_cvt_pk_bf16_f32 v150, v80, v81
	v_pk_mul_f32 v[84:85], v[86:87], v[138:139] op_sel_hi:[1,0]
	s_nop 0
	v_exp_f32_e32 v84, v84
	v_exp_f32_e32 v85, v85
	s_nop 0
	v_pk_add_f32 v[84:85], v[84:85], v[172:173] op_sel_hi:[1,0]
	s_nop 0
	v_rcp_f32_e32 v84, v84
	v_rcp_f32_e32 v85, v85
	s_nop 0
	v_pk_mul_f32 v[84:85], v[86:87], v[84:85]
	s_nop 0
	v_pk_mul_f32 v[82:83], v[82:83], v[84:85]
	s_nop 0
	v_cvt_pk_bf16_f32 v151, v82, v83
	s_nop 1
	v_permlane16_swap_b32_e32 v148, v150
	v_permlane16_swap_b32_e32 v149, v151
	global_store_dwordx4 v[90:91], v[148:151], off
	v_pk_mul_f32 v[80:81], v[76:77], v[138:139] op_sel_hi:[1,0]
	s_nop 0
	v_exp_f32_e32 v80, v80
	v_exp_f32_e32 v81, v81
	v_or_b32_e32 v82, 48, v128
	v_pk_add_f32 v[80:81], v[80:81], v[172:173] op_sel_hi:[1,0]
	s_nop 0
	v_rcp_f32_e32 v80, v80
	v_rcp_f32_e32 v81, v81
	s_nop 0
	v_pk_mul_f32 v[76:77], v[76:77], v[80:81]
	s_nop 0
	v_pk_mul_f32 v[72:73], v[72:73], v[76:77]
	s_nop 0
	v_cvt_pk_bf16_f32 v152, v72, v73
	v_pk_mul_f32 v[76:77], v[78:79], v[138:139] op_sel_hi:[1,0]
	s_nop 0
	v_exp_f32_e32 v76, v76
	v_exp_f32_e32 v77, v77
	s_nop 0
	v_pk_add_f32 v[76:77], v[76:77], v[172:173] op_sel_hi:[1,0]
	s_nop 0
	v_rcp_f32_e32 v76, v76
	v_rcp_f32_e32 v77, v77
	s_nop 0
	v_pk_mul_f32 v[76:77], v[78:79], v[76:77]
	s_nop 0
	v_pk_mul_f32 v[74:75], v[74:75], v[76:77]
	s_nop 0
	v_cvt_pk_bf16_f32 v153, v74, v75
	v_mad_i64_i32 v[74:75], s[0:1], v82, s3, v[120:121]
	v_lshl_add_u64 v[74:75], v[74:75], 0, v[122:123]
	v_pk_mul_f32 v[72:73], v[68:69], v[138:139] op_sel_hi:[1,0]
	s_nop 0
	v_exp_f32_e32 v72, v72
	v_exp_f32_e32 v73, v73
	s_nop 0
	v_pk_add_f32 v[72:73], v[72:73], v[172:173] op_sel_hi:[1,0]
	s_nop 0
	v_rcp_f32_e32 v72, v72
	v_rcp_f32_e32 v73, v73
	s_nop 0
	v_pk_mul_f32 v[68:69], v[68:69], v[72:73]
	s_nop 0
	v_pk_mul_f32 v[64:65], v[64:65], v[68:69]
	s_nop 0
	v_cvt_pk_bf16_f32 v154, v64, v65
	v_pk_mul_f32 v[68:69], v[70:71], v[138:139] op_sel_hi:[1,0]
	s_nop 0
	v_exp_f32_e32 v68, v68
	v_exp_f32_e32 v69, v69
	s_nop 0
	v_pk_add_f32 v[68:69], v[68:69], v[172:173] op_sel_hi:[1,0]
	s_nop 0
	v_rcp_f32_e32 v68, v68
	v_rcp_f32_e32 v69, v69
	s_nop 0
	v_pk_mul_f32 v[68:69], v[70:71], v[68:69]
	s_nop 0
	v_pk_mul_f32 v[66:67], v[66:67], v[68:69]
	s_nop 0
	v_cvt_pk_bf16_f32 v155, v66, v67
	s_nop 1
	v_permlane16_swap_b32_e32 v152, v154
	v_permlane16_swap_b32_e32 v153, v155
	global_store_dwordx4 v[74:75], v[152:155], off
	v_pk_mul_f32 v[64:65], v[60:61], v[138:139] op_sel_hi:[1,0]
	s_nop 0
	v_exp_f32_e32 v64, v64
	v_exp_f32_e32 v65, v65
	v_add_u32_e32 v66, 0x80, v128
	v_pk_add_f32 v[64:65], v[64:65], v[172:173] op_sel_hi:[1,0]
	s_nop 0
	v_rcp_f32_e32 v64, v64
	v_rcp_f32_e32 v65, v65
	s_nop 0
	v_pk_mul_f32 v[60:61], v[60:61], v[64:65]
	s_nop 0
	v_pk_mul_f32 v[56:57], v[56:57], v[60:61]
	s_nop 0
	v_cvt_pk_bf16_f32 v156, v56, v57
	v_pk_mul_f32 v[60:61], v[62:63], v[138:139] op_sel_hi:[1,0]
	s_nop 0
	v_exp_f32_e32 v60, v60
	v_exp_f32_e32 v61, v61
	s_nop 0
	v_pk_add_f32 v[60:61], v[60:61], v[172:173] op_sel_hi:[1,0]
	s_nop 0
	v_rcp_f32_e32 v60, v60
	v_rcp_f32_e32 v61, v61
	s_nop 0
	v_pk_mul_f32 v[60:61], v[62:63], v[60:61]
	s_nop 0
	v_pk_mul_f32 v[58:59], v[58:59], v[60:61]
	s_nop 0
	v_cvt_pk_bf16_f32 v157, v58, v59
	v_mad_i64_i32 v[58:59], s[0:1], v66, s3, v[120:121]
	v_lshl_add_u64 v[58:59], v[58:59], 0, v[122:123]
	v_pk_mul_f32 v[56:57], v[52:53], v[138:139] op_sel_hi:[1,0]
	s_nop 0
	v_exp_f32_e32 v56, v56
	v_exp_f32_e32 v57, v57
	s_nop 0
	v_pk_add_f32 v[56:57], v[56:57], v[172:173] op_sel_hi:[1,0]
	s_nop 0
	v_rcp_f32_e32 v56, v56
	v_rcp_f32_e32 v57, v57
	s_nop 0
	v_pk_mul_f32 v[52:53], v[52:53], v[56:57]
	s_nop 0
	v_pk_mul_f32 v[48:49], v[48:49], v[52:53]
	s_nop 0
	v_cvt_pk_bf16_f32 v158, v48, v49
	v_pk_mul_f32 v[52:53], v[54:55], v[138:139] op_sel_hi:[1,0]
	s_nop 0
	v_exp_f32_e32 v52, v52
	v_exp_f32_e32 v53, v53
	s_nop 0
	v_pk_add_f32 v[52:53], v[52:53], v[172:173] op_sel_hi:[1,0]
	s_nop 0
	v_rcp_f32_e32 v52, v52
	v_rcp_f32_e32 v53, v53
	s_nop 0
	v_pk_mul_f32 v[52:53], v[54:55], v[52:53]
	s_nop 0
	v_pk_mul_f32 v[50:51], v[50:51], v[52:53]
	s_nop 0
	v_cvt_pk_bf16_f32 v159, v50, v51
	s_nop 1
	v_permlane16_swap_b32_e32 v156, v158
	v_permlane16_swap_b32_e32 v157, v159
	global_store_dwordx4 v[58:59], v[156:159], off
	v_pk_mul_f32 v[48:49], v[44:45], v[138:139] op_sel_hi:[1,0]
	s_nop 0
	v_exp_f32_e32 v48, v48
	v_exp_f32_e32 v49, v49
	v_add_u32_e32 v50, 0x90, v128
	v_pk_add_f32 v[48:49], v[48:49], v[172:173] op_sel_hi:[1,0]
	s_nop 0
	v_rcp_f32_e32 v48, v48
	v_rcp_f32_e32 v49, v49
	s_nop 0
	v_pk_mul_f32 v[44:45], v[44:45], v[48:49]
	s_nop 0
	v_pk_mul_f32 v[40:41], v[40:41], v[44:45]
	s_nop 0
	v_cvt_pk_bf16_f32 v160, v40, v41
	v_pk_mul_f32 v[44:45], v[46:47], v[138:139] op_sel_hi:[1,0]
	s_nop 0
	v_exp_f32_e32 v44, v44
	v_exp_f32_e32 v45, v45
	s_nop 0
; __device__ __forceinline__ unsigned pk2(float lo, float hi) { const f32x2v v = {lo, hi}; const bf16x2v r = __builtin_convertvector(v, bf16x2v); return __builtin_bit_cast(unsigned, r); }
; __device__ __forceinline__ float silu_f(float x) { return x * __builtin_amdgcn_rcpf(1.f + __expf(-x)); }
; #define GEMM_EPI_LOOP _Pragma("unroll") for (int ai = 0; ai < 2; ++ai) _Pragma("unroll") for (int m = 0; m < 4; ++m) _Pragma("unroll") for (int bj = 0; bj < 2; ++bj)
; __device__ __forceinline__ void gemm_up_phase(const bf16_t* a, const bf16_t* wgu, bf16_t* act, char* lds) {
;   gemm_phase(a, 1024, wgu, 1024, 1024, NGU / 256, lds, [&](f32x4 (&acc)[2][2][4][2], int tm, int tn) {
;     GEMM_LANE;
;     GEMM_EPI_LOOP {
;       const int row = tm * 256 + ai * 128 + wr * 64 + m * 16 + fr;
;       const int col = tn * 128 + bj * 64 + wc * 16 + 4 * fq;
;       const f32x4 g = acc[ai][bj][m][0], u = acc[ai][bj][m][1];
;       u32x2 o; o.x = pk2(silu_f(g[0]) * u[0], silu_f(g[1]) * u[1]); o.y = pk2(silu_f(g[2]) * u[2], silu_f(g[3]) * u[3]);
;       *(u32x2*)(act + (size_t)row * DFF + col) = o;
;     }
	v_pk_add_f32 v[44:45], v[44:45], v[172:173] op_sel_hi:[1,0]
	s_nop 0
	v_rcp_f32_e32 v44, v44
	v_rcp_f32_e32 v45, v45
	s_nop 0
	v_pk_mul_f32 v[44:45], v[46:47], v[44:45]
	s_nop 0
	v_pk_mul_f32 v[42:43], v[42:43], v[44:45]
	s_nop 0
	v_cvt_pk_bf16_f32 v161, v42, v43
	v_mad_i64_i32 v[42:43], s[0:1], v50, s3, v[120:121]
	v_lshl_add_u64 v[42:43], v[42:43], 0, v[122:123]
	v_pk_mul_f32 v[40:41], v[36:37], v[138:139] op_sel_hi:[1,0]
	s_nop 0
	v_exp_f32_e32 v40, v40
	v_exp_f32_e32 v41, v41
	s_nop 0
	v_pk_add_f32 v[40:41], v[40:41], v[172:173] op_sel_hi:[1,0]
	s_nop 0
	v_rcp_f32_e32 v40, v40
	v_rcp_f32_e32 v41, v41
	s_nop 0
	v_pk_mul_f32 v[36:37], v[36:37], v[40:41]
	s_nop 0
	v_pk_mul_f32 v[32:33], v[32:33], v[36:37]
	s_nop 0
	v_cvt_pk_bf16_f32 v162, v32, v33
	v_pk_mul_f32 v[36:37], v[38:39], v[138:139] op_sel_hi:[1,0]
	s_nop 0
	v_exp_f32_e32 v36, v36
	v_exp_f32_e32 v37, v37
	s_nop 0
	v_pk_add_f32 v[36:37], v[36:37], v[172:173] op_sel_hi:[1,0]
	s_nop 0
	v_rcp_f32_e32 v36, v36
	v_rcp_f32_e32 v37, v37
	s_nop 0
	v_pk_mul_f32 v[36:37], v[38:39], v[36:37]
	s_nop 0
	v_pk_mul_f32 v[34:35], v[34:35], v[36:37]
	s_nop 0
	v_cvt_pk_bf16_f32 v163, v34, v35
	s_nop 1
	v_permlane16_swap_b32_e32 v160, v162
	v_permlane16_swap_b32_e32 v161, v163
	global_store_dwordx4 v[42:43], v[160:163], off
	v_pk_mul_f32 v[32:33], v[28:29], v[138:139] op_sel_hi:[1,0]
	s_nop 0
	v_exp_f32_e32 v32, v32
	v_exp_f32_e32 v33, v33
	v_add_u32_e32 v34, 0xa0, v128
	v_pk_add_f32 v[32:33], v[32:33], v[172:173] op_sel_hi:[1,0]
	s_nop 0
	v_rcp_f32_e32 v32, v32
	v_rcp_f32_e32 v33, v33
	s_nop 0
	v_pk_mul_f32 v[28:29], v[28:29], v[32:33]
	s_nop 0
	v_pk_mul_f32 v[24:25], v[24:25], v[28:29]
	s_nop 0
	v_cvt_pk_bf16_f32 v164, v24, v25
	v_pk_mul_f32 v[28:29], v[30:31], v[138:139] op_sel_hi:[1,0]
	s_nop 0
	v_exp_f32_e32 v28, v28
	v_exp_f32_e32 v29, v29
	s_nop 0
	v_pk_add_f32 v[28:29], v[28:29], v[172:173] op_sel_hi:[1,0]
	s_nop 0
	v_rcp_f32_e32 v28, v28
	v_rcp_f32_e32 v29, v29
	s_nop 0
	v_pk_mul_f32 v[28:29], v[30:31], v[28:29]
	s_nop 0
	v_pk_mul_f32 v[26:27], v[26:27], v[28:29]
	s_nop 0
	v_cvt_pk_bf16_f32 v165, v26, v27
	v_mad_i64_i32 v[26:27], s[0:1], v34, s3, v[120:121]
	v_lshl_add_u64 v[26:27], v[26:27], 0, v[122:123]
	v_pk_mul_f32 v[24:25], v[20:21], v[138:139] op_sel_hi:[1,0]
	s_nop 0
	v_exp_f32_e32 v24, v24
	v_exp_f32_e32 v25, v25
	s_nop 0
	v_pk_add_f32 v[24:25], v[24:25], v[172:173] op_sel_hi:[1,0]
	s_nop 0
	v_rcp_f32_e32 v24, v24
	v_rcp_f32_e32 v25, v25
	s_nop 0
	v_pk_mul_f32 v[20:21], v[20:21], v[24:25]
	s_nop 0
	v_pk_mul_f32 v[16:17], v[16:17], v[20:21]
	s_nop 0
	v_cvt_pk_bf16_f32 v166, v16, v17
	v_pk_mul_f32 v[20:21], v[22:23], v[138:139] op_sel_hi:[1,0]
	s_nop 0
	v_exp_f32_e32 v20, v20
	v_exp_f32_e32 v21, v21
	s_nop 0
	v_pk_add_f32 v[20:21], v[20:21], v[172:173] op_sel_hi:[1,0]
	s_nop 0
	v_rcp_f32_e32 v20, v20
	v_rcp_f32_e32 v21, v21
	s_nop 0
	v_pk_mul_f32 v[20:21], v[22:23], v[20:21]
	s_nop 0
	v_pk_mul_f32 v[18:19], v[18:19], v[20:21]
	s_nop 0
	v_cvt_pk_bf16_f32 v167, v18, v19
	s_nop 1
	v_permlane16_swap_b32_e32 v164, v166
	v_permlane16_swap_b32_e32 v165, v167
	global_store_dwordx4 v[26:27], v[164:167], off
	v_pk_mul_f32 v[16:17], v[12:13], v[138:139] op_sel_hi:[1,0]
	s_nop 0
	v_exp_f32_e32 v16, v16
	v_exp_f32_e32 v17, v17
	v_add_u32_e32 v18, 0xb0, v128
	v_pk_add_f32 v[16:17], v[16:17], v[172:173] op_sel_hi:[1,0]
	s_nop 0
	v_rcp_f32_e32 v16, v16
	v_rcp_f32_e32 v17, v17
	s_nop 0
	v_pk_mul_f32 v[12:13], v[12:13], v[16:17]
	s_nop 0
	v_pk_mul_f32 v[8:9], v[8:9], v[12:13]
	s_nop 0
	v_cvt_pk_bf16_f32 v168, v8, v9
	v_pk_mul_f32 v[12:13], v[14:15], v[138:139] op_sel_hi:[1,0]
	s_nop 0
	v_exp_f32_e32 v12, v12
	v_exp_f32_e32 v13, v13
	s_nop 0
	v_pk_add_f32 v[12:13], v[12:13], v[172:173] op_sel_hi:[1,0]
	s_nop 0
	v_rcp_f32_e32 v12, v12
	v_rcp_f32_e32 v13, v13
	s_nop 0
	v_pk_mul_f32 v[12:13], v[14:15], v[12:13]
	s_nop 0
	v_pk_mul_f32 v[10:11], v[10:11], v[12:13]
	s_nop 0
	v_cvt_pk_bf16_f32 v169, v10, v11
	v_mad_i64_i32 v[10:11], s[0:1], v18, s3, v[120:121]
	v_lshl_add_u64 v[10:11], v[10:11], 0, v[122:123]
	v_pk_mul_f32 v[8:9], v[4:5], v[138:139] op_sel_hi:[1,0]
	s_nop 0
	v_exp_f32_e32 v8, v8
	v_exp_f32_e32 v9, v9
	s_mov_b32 s0, s30
	v_pk_add_f32 v[8:9], v[8:9], v[172:173] op_sel_hi:[1,0]
	s_nop 0
	v_rcp_f32_e32 v8, v8
	v_rcp_f32_e32 v9, v9
	s_nop 0
	v_pk_mul_f32 v[4:5], v[4:5], v[8:9]
	s_nop 0
	v_pk_mul_f32 v[0:1], v[0:1], v[4:5]
	s_nop 0
	v_cvt_pk_bf16_f32 v170, v0, v1
	v_pk_mul_f32 v[4:5], v[6:7], v[138:139] op_sel_hi:[1,0]
	s_nop 0
	v_exp_f32_e32 v4, v4
	v_exp_f32_e32 v5, v5
	s_nop 0
	v_pk_add_f32 v[4:5], v[4:5], v[172:173] op_sel_hi:[1,0]
	s_nop 0
	v_rcp_f32_e32 v4, v4
	v_rcp_f32_e32 v5, v5
	s_nop 0
	v_pk_mul_f32 v[4:5], v[6:7], v[4:5]
	s_nop 0
	v_pk_mul_f32 v[2:3], v[2:3], v[4:5]
	s_nop 0
	v_cvt_pk_bf16_f32 v171, v2, v3
	s_nop 1
	v_permlane16_swap_b32_e32 v168, v170
	v_permlane16_swap_b32_e32 v169, v171
	global_store_dwordx4 v[10:11], v[168:171], off
	s_nop 1
	s_cbranch_vccz .LBB0_660
